# P0 x-rows loop: peel first next-row load issue, drop per-load vmcnt waits at loop top, single vmcnt(9) before register rotation
# baseline (speedup 1.0000x reference)
.LBB0_30:
	s_cmp_eq_u32 s100, 1
	s_cbranch_scc1 .Ldf_ret_p1
	s_cmp_eq_u32 s100, 2
	s_cbranch_scc1 .Ldf_ret_p3
	s_add_u32 s6, s92, 0x4d00000
	s_addc_u32 s7, s93, 0
	s_cmpk_gt_i32 s26, 0x3fff
	v_lshlrev_b32_e32 v66, 4, v76
	v_cmp_ne_u32_e64 s[4:5], 0, v76
	v_lshlrev_b32_e32 v68, 3, v76
	s_cbranch_scc1 .LBB0_40
	s_ashr_i32 s27, s26, 31
	s_lshl_b64 s[0:1], s[26:27], 13
	v_readlane_b32 s40, v233, 2
	v_readlane_b32 s41, v233, 3
	s_add_u32 s0, s40, s0
	s_addc_u32 s1, s41, s1
	v_mov_b32_e32 v67, 0
	v_lshl_add_u64 v[2:3], s[0:1], 0, v[66:67]
	global_load_dwordx4 v[62:65], v66, s[0:1] nt
	global_load_dwordx4 v[58:61], v66, s[0:1] offset:1024 nt
	global_load_dwordx4 v[54:57], v66, s[0:1] offset:2048 nt
	global_load_dwordx4 v[46:49], v66, s[0:1] offset:3072 nt
	s_movk_i32 s0, 0x1000
	v_add_co_u32_e32 v2, vcc, s0, v2
	s_lshl_b64 s[0:1], s[26:27], 2
	s_nop 0
	v_addc_co_u32_e32 v3, vcc, 0, v3, vcc
	global_load_dwordx4 v[50:53], v[2:3], off nt
	global_load_dwordx4 v[42:45], v[2:3], off offset:1024 nt
	global_load_dwordx4 v[38:41], v[2:3], off offset:2048 nt
	global_load_dwordx4 v[34:37], v[2:3], off offset:3072 nt
	s_add_u32 s8, s92, s0
	v_mov_b32_e32 v69, v67
	s_addc_u32 s9, s93, s1
	s_ashr_i32 s97, s96, 31
	v_lshl_add_u64 v[70:71], s[40:41], 0, v[66:67]
	v_lshl_add_u64 v[72:73], s[6:7], 0, v[68:69]
	s_lshl_b64 s[10:11], s[96:97], 2
	v_mov_b32_e32 v69, 0x358637bd
	s_mov_b32 s17, 0xf800000
	v_mov_b32_e32 v77, 0x260
	s_mov_b64 s[12:13], s[26:27]
	v_readlane_b32 s42, v233, 4
	v_readlane_b32 s43, v233, 5
	v_readlane_b32 s44, v233, 6
	v_readlane_b32 s45, v233, 7
	v_readlane_b32 s46, v233, 8
	v_readlane_b32 s47, v233, 9
	v_readlane_b32 s48, v233, 10
	v_readlane_b32 s49, v233, 11
	v_readlane_b32 s50, v233, 12
	v_readlane_b32 s51, v233, 13
	v_readlane_b32 s52, v233, 14
	v_readlane_b32 s53, v233, 15
	v_readlane_b32 s54, v233, 16
	v_readlane_b32 s55, v233, 17
	s_add_i32 s0, s96, s12
	s_cmpk_gt_i32 s0, 0x3fff
	s_cbranch_scc1 .Lp0x_first_nl
	s_ashr_i32 s1, s0, 31
	s_lshl_b64 s[0:1], s[0:1], 13
	v_lshl_add_u64 v[18:19], v[70:71], 0, s[0:1]
	global_load_dwordx4 v[14:17], v[18:19], off nt
	global_load_dwordx4 v[10:13], v[18:19], off offset:1024 nt
	global_load_dwordx4 v[6:9], v[18:19], off offset:2048 nt
	global_load_dwordx4 v[2:5], v[18:19], off offset:3072 nt
	v_add_co_u32_e32 v18, vcc, 0x1000, v18
	s_nop 1
	v_addc_co_u32_e32 v19, vcc, 0, v19, vcc
	global_load_dwordx4 v[30:33], v[18:19], off nt
	global_load_dwordx4 v[26:29], v[18:19], off offset:1024 nt
	global_load_dwordx4 v[22:25], v[18:19], off offset:2048 nt
	s_nop 0
	global_load_dwordx4 v[18:21], v[18:19], off offset:3072 nt
	s_waitcnt vmcnt(8)
	s_branch .LBB0_35
.Lp0x_first_nl:
	s_waitcnt vmcnt(0)
	s_branch .LBB0_35
.LBB0_32:
	s_or_b64 exec, exec, s[14:15]
	s_add_u32 s12, s12, s96
	v_lshlrev_b64 v[74:75], 12, v[74:75]
	s_addc_u32 s13, s13, s97
	v_lshl_add_u64 v[74:75], v[72:73], 0, v[74:75]
	v_cvt_pk_bf16_f32 v62, v62, v63
	v_cvt_pk_bf16_f32 v63, v64, v65
	global_store_dwordx2 v[74:75], v[62:63], off
	v_cvt_pk_bf16_f32 v58, v58, v59
	v_cvt_pk_bf16_f32 v59, v60, v61
	global_store_dwordx2 v[74:75], v[58:59], off offset:512
	v_cvt_pk_bf16_f32 v54, v54, v55
	v_cvt_pk_bf16_f32 v55, v56, v57
	global_store_dwordx2 v[74:75], v[54:55], off offset:1024
	v_cvt_pk_bf16_f32 v46, v46, v47
	v_cvt_pk_bf16_f32 v47, v48, v49
	s_add_u32 s8, s8, s10
	global_store_dwordx2 v[74:75], v[46:47], off offset:1536
	v_cvt_pk_bf16_f32 v46, v50, v51
	v_cvt_pk_bf16_f32 v47, v52, v53
	global_store_dwordx2 v[74:75], v[46:47], off offset:2048
	v_cvt_pk_bf16_f32 v42, v42, v43
	v_cvt_pk_bf16_f32 v43, v44, v45
	global_store_dwordx2 v[74:75], v[42:43], off offset:2560
	v_cvt_pk_bf16_f32 v38, v38, v39
	v_cvt_pk_bf16_f32 v39, v40, v41
	global_store_dwordx2 v[74:75], v[38:39], off offset:3072
	v_cvt_pk_bf16_f32 v34, v34, v35
	v_cvt_pk_bf16_f32 v35, v36, v37
	s_addc_u32 s9, s9, s11
	global_store_dwordx2 v[74:75], v[34:35], off offset:3584
	s_cmpk_lt_i32 s12, 0x4000
	s_waitcnt vmcnt(9)
	v_mov_b32_e32 v62, v14
	v_mov_b32_e32 v63, v15
	v_mov_b32_e32 v64, v16
	v_mov_b32_e32 v65, v17
	v_mov_b32_e32 v58, v10
	v_mov_b32_e32 v59, v11
	v_mov_b32_e32 v60, v12
	v_mov_b32_e32 v61, v13
	v_mov_b32_e32 v54, v6
	v_mov_b32_e32 v55, v7
	v_mov_b32_e32 v56, v8
	v_mov_b32_e32 v57, v9
	v_mov_b32_e32 v46, v2
	v_mov_b32_e32 v47, v3
	v_mov_b32_e32 v48, v4
	v_mov_b32_e32 v49, v5
	v_mov_b32_e32 v50, v30
	v_mov_b32_e32 v51, v31
	v_mov_b32_e32 v52, v32
	v_mov_b32_e32 v53, v33
	v_mov_b32_e32 v42, v26
	v_mov_b32_e32 v43, v27
	v_mov_b32_e32 v44, v28
	v_mov_b32_e32 v45, v29
	v_mov_b32_e32 v38, v22
	v_mov_b32_e32 v39, v23
	v_mov_b32_e32 v40, v24
	v_mov_b32_e32 v41, v25
	v_mov_b32_e32 v34, v18
	v_mov_b32_e32 v35, v19
	v_mov_b32_e32 v36, v20
	v_mov_b32_e32 v37, v21
	s_cbranch_scc0 .LBB0_39

.LBB0_35:
	v_mul_f32_e32 v74, v63, v63
	v_mul_f32_e32 v75, v65, v65
	v_fmac_f32_e32 v74, v62, v62
	v_fmac_f32_e32 v75, v64, v64
	v_add_f32_e32 v74, v74, v75
	v_mul_f32_e32 v75, v59, v59
	v_mul_f32_e32 v78, v61, v61
	v_fmac_f32_e32 v75, v58, v58
	v_fmac_f32_e32 v78, v60, v60
	v_add_f32_e32 v75, v75, v78
	v_add_f32_e32 v74, v74, v75
	v_mul_f32_e32 v75, v55, v55
	v_mul_f32_e32 v78, v57, v57
	v_fmac_f32_e32 v75, v54, v54
	v_fmac_f32_e32 v78, v56, v56
	v_add_f32_e32 v75, v75, v78
	v_add_f32_e32 v74, v75, v74
	v_mul_f32_e32 v75, v47, v47
	v_mul_f32_e32 v78, v49, v49
	v_fmac_f32_e32 v75, v46, v46
	v_fmac_f32_e32 v78, v48, v48
	v_add_f32_e32 v75, v75, v78
	v_add_f32_e32 v74, v75, v74
	v_mul_f32_e32 v75, v51, v51
	v_mul_f32_e32 v78, v53, v53
	v_fmac_f32_e32 v75, v50, v50
	v_fmac_f32_e32 v78, v52, v52
	v_add_f32_e32 v75, v75, v78
	v_add_f32_e32 v74, v75, v74
	v_mul_f32_e32 v75, v43, v43
	v_mul_f32_e32 v78, v45, v45
	v_fmac_f32_e32 v75, v42, v42
	v_fmac_f32_e32 v78, v44, v44
	v_add_f32_e32 v75, v75, v78
	v_add_f32_e32 v74, v75, v74
	v_mul_f32_e32 v75, v39, v39
	v_mul_f32_e32 v78, v41, v41
	v_fmac_f32_e32 v75, v38, v38
	v_fmac_f32_e32 v78, v40, v40
	v_add_f32_e32 v75, v75, v78
	v_add_f32_e32 v74, v75, v74
	v_mul_f32_e32 v75, v35, v35
	v_mul_f32_e32 v78, v37, v37
	v_fmac_f32_e32 v75, v34, v34
	v_fmac_f32_e32 v78, v36, v36
	v_add_f32_e32 v75, v75, v78
	v_add_f32_e32 v74, v75, v74
	s_nop 1
	v_add_f32_dpp v74, v74, v74 quad_perm:[1,0,3,2] row_mask:0xf bank_mask:0xf bound_ctrl:1
	s_nop 1
	v_add_f32_dpp v74, v74, v74 quad_perm:[2,3,0,1] row_mask:0xf bank_mask:0xf bound_ctrl:1
	s_nop 1
	v_add_f32_dpp v74, v74, v74 row_ror:4 row_mask:0xf bank_mask:0xf bound_ctrl:1
	s_nop 1
	v_add_f32_dpp v74, v74, v74 row_ror:8 row_mask:0xf bank_mask:0xf bound_ctrl:1
	v_mov_b32_e32 v75, v74
	s_nop 1
	v_permlane16_swap_b32_e32 v74, v75
	v_add_f32_e32 v78, v74, v75
	v_mov_b32_e32 v79, v78
	s_nop 1
	v_permlane32_swap_b32_e32 v78, v79
	s_and_saveexec_b64 s[14:15], s[4:5]
	s_xor_b64 s[14:15], exec, s[14:15]
	s_bfe_i64 s[0:1], s[12:13], 0x200000
	s_or_saveexec_b64 s[14:15], s[14:15]
	v_mov_b64_e32 v[74:75], s[0:1]
	s_xor_b64 exec, exec, s[14:15]
	s_cbranch_execz .LBB0_32
	v_add_f32_e32 v74, v78, v79
	v_fmamk_f32 v74, v74, 0x3a000000, v69
	v_mul_f32_e32 v75, 0x4f800000, v74
	v_cmp_gt_f32_e32 vcc, s17, v74
	s_nop 1
	v_cndmask_b32_e32 v74, v74, v75, vcc
	v_sqrt_f32_e32 v75, v74
	s_nop 0
	v_add_u32_e32 v78, -1, v75
	v_fma_f32 v80, -v78, v75, v74
	v_add_u32_e32 v79, 1, v75
	v_cmp_ge_f32_e64 s[0:1], 0, v80
	s_nop 1
	v_cndmask_b32_e64 v78, v75, v78, s[0:1]
	v_fma_f32 v75, -v79, v75, v74
	v_cmp_lt_f32_e64 s[0:1], 0, v75
	s_nop 1
	v_cndmask_b32_e64 v75, v78, v79, s[0:1]
	v_mul_f32_e32 v78, 0x37800000, v75
	v_cndmask_b32_e32 v75, v75, v78, vcc
	v_cmp_class_f32_e32 vcc, v74, v77
	s_nop 1
	v_cndmask_b32_e32 v74, v75, v74, vcc
	v_div_scale_f32 v75, s[0:1], v74, v74, 1.0
	v_rcp_f32_e32 v78, v75
	s_nop 0
	v_fma_f32 v79, -v75, v78, 1.0
	v_fmac_f32_e32 v78, v79, v78
	v_div_scale_f32 v79, vcc, 1.0, v74, 1.0
	v_mul_f32_e32 v80, v79, v78
	v_fma_f32 v81, -v75, v80, v79
	v_fmac_f32_e32 v80, v81, v78
	v_fma_f32 v75, -v75, v80, v79
	v_div_fmas_f32 v75, v75, v78, v80
	v_div_fixup_f32 v74, v75, v74, 1.0
	global_store_dword v67, v74, s[8:9]
	v_mov_b64_e32 v[74:75], s[12:13]
	s_branch .LBB0_32
